# gemm1 epilogue: xor-16/32 row-norm reductions via v_permlane16/32_swap instead of ds_bpermute round trips
# speedup vs baseline: 1.0047x; 1.0047x over previous
.LBB0_520:
	s_lshr_b32 s16, s16, 7
	s_add_i32 s16, s16, -12
	s_and_b64 s[26:27], s[40:41], exec
	s_cselect_b32 s21, 2, -1
	s_cmpk_lg_i32 s17, 0xc00
	s_cselect_b32 s21, s21, 1
	s_cmp_lt_u32 s16, 8
	s_cselect_b64 s[40:41], -1, 0
	s_and_b64 s[16:17], s[40:41], exec
	s_cselect_b32 s36, 0, s21
	s_cmp_gt_i32 s36, -1
	s_cselect_b64 s[64:65], -1, 0
	s_cmp_lt_i32 s36, 0
	s_cbranch_scc1 .LBB0_522
	v_mul_f32_e32 v127, v127, v127
	v_mul_f32_e32 v119, v119, v119
	v_fmac_f32_e32 v127, v126, v126
	v_fmac_f32_e32 v119, v118, v118
	v_fmac_f32_e32 v127, v128, v128
	v_fmac_f32_e32 v119, v120, v120
	v_fmac_f32_e32 v127, v129, v129
	v_fmac_f32_e32 v119, v121, v121
	v_fmac_f32_e32 v127, v122, v122
	v_fmac_f32_e32 v119, v114, v114
	v_fmac_f32_e32 v127, v123, v123
	v_fmac_f32_e32 v119, v115, v115
	v_fmac_f32_e32 v127, v124, v124
	v_fmac_f32_e32 v119, v116, v116
	v_cmp_lt_i32_e32 vcc, v185, v183
	v_fmac_f32_e32 v127, v125, v125
	v_fmac_f32_e32 v119, v117, v117
	v_cndmask_b32_e32 v115, v182, v185, vcc
	v_add_f32_e32 v114, v127, v119
	v_lshlrev_b32_e32 v115, 2, v115
	v_mov_b32_e32 v115, v114
	s_nop 1
	v_permlane16_swap_b32_e32 v114, v115
	v_cmp_lt_i32_e32 vcc, v184, v183
	s_waitcnt lgkmcnt(0)
	v_add_f32_e32 v114, v114, v115
	v_cndmask_b32_e32 v115, v182, v184, vcc
	v_lshlrev_b32_e32 v115, 2, v115
	v_mov_b32_e32 v115, v114
	s_nop 1
	v_permlane32_swap_b32_e32 v114, v115
	s_waitcnt lgkmcnt(0)
	v_add_f32_e32 v114, v114, v115
	v_max_f32_e32 v122, 0, v114
	s_branch .LBB0_523

.LBB0_568:
	v_mul_f32_e32 v111, v111, v111
	v_mul_f32_e32 v103, v103, v103
	v_fmac_f32_e32 v111, v110, v110
	v_fmac_f32_e32 v103, v102, v102
	v_fmac_f32_e32 v111, v112, v112
	v_fmac_f32_e32 v103, v104, v104
	v_fmac_f32_e32 v111, v113, v113
	v_fmac_f32_e32 v103, v105, v105
	v_fmac_f32_e32 v111, v106, v106
	v_fmac_f32_e32 v103, v98, v98
	v_fmac_f32_e32 v111, v107, v107
	v_fmac_f32_e32 v103, v99, v99
	v_fmac_f32_e32 v111, v108, v108
	v_fmac_f32_e32 v103, v100, v100
	v_cmp_lt_i32_e32 vcc, v185, v183
	v_fmac_f32_e32 v111, v109, v109
	v_fmac_f32_e32 v103, v101, v101
	v_cndmask_b32_e32 v99, v182, v185, vcc
	v_add_f32_e32 v98, v111, v103
	v_lshlrev_b32_e32 v99, 2, v99
	v_mov_b32_e32 v99, v98
	s_nop 1
	v_permlane16_swap_b32_e32 v98, v99
	v_cmp_lt_i32_e32 vcc, v184, v183
	s_waitcnt lgkmcnt(0)
	v_add_f32_e32 v98, v98, v99
	v_cndmask_b32_e32 v99, v182, v184, vcc
	v_lshlrev_b32_e32 v99, 2, v99
	v_mov_b32_e32 v99, v98
	s_nop 1
	v_permlane32_swap_b32_e32 v98, v99
	s_waitcnt lgkmcnt(0)
	v_add_f32_e32 v98, v98, v99
	v_max_f32_e32 v99, v122, v122
	v_max_f32_e32 v122, v99, v98

.LBB0_614:
	v_mul_f32_e32 v95, v95, v95
	v_mul_f32_e32 v87, v87, v87
	v_fmac_f32_e32 v95, v94, v94
	v_fmac_f32_e32 v87, v86, v86
	v_fmac_f32_e32 v95, v96, v96
	v_fmac_f32_e32 v87, v88, v88
	v_fmac_f32_e32 v95, v97, v97
	v_fmac_f32_e32 v87, v89, v89
	v_fmac_f32_e32 v95, v90, v90
	v_fmac_f32_e32 v87, v82, v82
	v_fmac_f32_e32 v95, v91, v91
	v_fmac_f32_e32 v87, v83, v83
	v_fmac_f32_e32 v95, v92, v92
	v_fmac_f32_e32 v87, v84, v84
	v_cmp_lt_i32_e32 vcc, v185, v183
	v_fmac_f32_e32 v95, v93, v93
	v_fmac_f32_e32 v87, v85, v85
	v_cndmask_b32_e32 v83, v182, v185, vcc
	v_add_f32_e32 v82, v95, v87
	v_lshlrev_b32_e32 v83, 2, v83
	v_mov_b32_e32 v83, v82
	s_nop 1
	v_permlane16_swap_b32_e32 v82, v83
	v_cmp_lt_i32_e32 vcc, v184, v183
	s_waitcnt lgkmcnt(0)
	v_add_f32_e32 v82, v82, v83
	v_cndmask_b32_e32 v83, v182, v184, vcc
	v_lshlrev_b32_e32 v83, 2, v83
	v_mov_b32_e32 v83, v82
	s_nop 1
	v_permlane32_swap_b32_e32 v82, v83
	s_waitcnt lgkmcnt(0)
	v_add_f32_e32 v82, v82, v83
	v_max_f32_e32 v83, v122, v122
	v_max_f32_e32 v122, v83, v82

.LBB0_658:
	v_mul_f32_e32 v0, v75, v75
	v_mul_f32_e32 v67, v67, v67
	v_fmac_f32_e32 v0, v74, v74
	v_fmac_f32_e32 v67, v66, v66
	v_fmac_f32_e32 v0, v76, v76
	v_fmac_f32_e32 v67, v68, v68
	v_fmac_f32_e32 v0, v77, v77
	v_fmac_f32_e32 v67, v69, v69
	v_fmac_f32_e32 v0, v70, v70
	v_fmac_f32_e32 v67, v78, v78
	v_fmac_f32_e32 v0, v71, v71
	v_fmac_f32_e32 v67, v79, v79
	v_fmac_f32_e32 v0, v72, v72
	v_fmac_f32_e32 v67, v80, v80
	v_cmp_lt_i32_e32 vcc, v185, v183
	v_fmac_f32_e32 v0, v73, v73
	v_fmac_f32_e32 v67, v81, v81
	v_cndmask_b32_e32 v66, v182, v185, vcc
	v_add_f32_e32 v0, v0, v67
	v_lshlrev_b32_e32 v66, 2, v66
	v_mov_b32_e32 v66, v0
	s_nop 1
	v_permlane16_swap_b32_e32 v0, v66
	v_cmp_lt_i32_e32 vcc, v184, v183
	s_waitcnt lgkmcnt(0)
	v_add_f32_e32 v0, v0, v66
	v_cndmask_b32_e32 v66, v182, v184, vcc
	v_lshlrev_b32_e32 v66, 2, v66
	v_mov_b32_e32 v66, v0
	s_nop 1
	v_permlane32_swap_b32_e32 v0, v66
	s_waitcnt lgkmcnt(0)
	v_add_f32_e32 v0, v0, v66
	v_max_f32_e32 v66, v122, v122
	v_max_f32_e32 v0, v66, v0
	v_xor_b32_e32 v66, 1, v182
	v_cmp_lt_i32_e32 vcc, v66, v183
	s_nop 1
	v_cndmask_b32_e32 v66, v182, v66, vcc
	v_lshlrev_b32_e32 v66, 2, v66
	ds_bpermute_b32 v66, v66, v0
	s_waitcnt lgkmcnt(0)
	v_max_f32_e32 v66, v66, v66
	v_max_f32_e32 v0, v0, v66
	v_xor_b32_e32 v66, 2, v182
	v_cmp_lt_i32_e32 vcc, v66, v183
	s_nop 1
	v_cndmask_b32_e32 v66, v182, v66, vcc
	v_lshlrev_b32_e32 v66, 2, v66
	ds_bpermute_b32 v66, v66, v0
	s_waitcnt lgkmcnt(0)
	v_max_f32_e32 v66, v66, v66
	v_max_f32_e32 v0, v0, v66
	v_xor_b32_e32 v66, 4, v182
	v_cmp_lt_i32_e32 vcc, v66, v183
	s_nop 1
	v_cndmask_b32_e32 v66, v182, v66, vcc
	v_lshlrev_b32_e32 v66, 2, v66
	ds_bpermute_b32 v66, v66, v0
	s_waitcnt lgkmcnt(0)
	v_max_f32_e32 v66, v66, v66
	v_max_f32_e32 v0, v0, v66
	v_xor_b32_e32 v66, 8, v182
	v_cmp_lt_i32_e32 vcc, v66, v183
	s_nop 1
	v_cndmask_b32_e32 v66, v182, v66, vcc
	v_lshlrev_b32_e32 v66, 2, v66
	ds_bpermute_b32 v66, v66, v0
	s_and_saveexec_b64 s[28:29], s[38:39]
	s_cbranch_execz .LBB0_663
	s_waitcnt lgkmcnt(0)
	v_max_f32_e32 v66, v66, v66
	v_max_f32_e32 v0, v0, v0
	v_max_f32_e32 v0, v0, v66
	v_mul_f32_e32 v66, 0x3d053526, v0
	v_cndmask_b32_e64 v0, v0, v66, s[40:41]
	s_mov_b32 s9, 0
	s_mov_b64 s[40:41], exec
